# row phases: the four gb gain loads issued together before the X stores, one wait instead of four serialized full waits
# speedup vs baseline: 1.0659x; 1.0076x over previous
.LBB0_520:
	v_mul_f32_e32 v36, v13, v13
	v_mul_f32_e32 v37, v9, v9
	v_mul_f32_e32 v38, v5, v5
	v_fmac_f32_e32 v36, v12, v12
	v_fmac_f32_e32 v37, v8, v8
	v_mul_f32_e32 v39, v1, v1
	v_fmac_f32_e32 v38, v4, v4
	v_fmac_f32_e32 v36, v14, v14
	v_fmac_f32_e32 v37, v10, v10
	v_fmac_f32_e32 v39, v0, v0
	v_fmac_f32_e32 v38, v6, v6
	v_fmac_f32_e32 v36, v15, v15
	v_fmac_f32_e32 v37, v11, v11
	v_fmac_f32_e32 v39, v2, v2
	v_fmac_f32_e32 v38, v7, v7
	v_add_f32_e32 v36, v36, v37
	v_fmac_f32_e32 v39, v3, v3
	v_add_f32_e32 v36, v38, v36
	v_add_f32_e32 v36, v39, v36
	v_lshl_add_u64 v[34:35], v[24:25], 0, v[18:19]
	v_add_co_u32_e64 v34, s[4:5], s23, v34
	v_add_f32_dpp v36, v36, v36 quad_perm:[1,0,3,2] row_mask:0xf bank_mask:0xf bound_ctrl:1
	s_nop 0
	v_addc_co_u32_e64 v35, s[4:5], 0, v35, s[4:5]
	v_add_f32_dpp v36, v36, v36 quad_perm:[2,3,0,1] row_mask:0xf bank_mask:0xf bound_ctrl:1
	v_add_u32_e32 v16, s56, v16
	v_lshl_add_u64 v[24:25], v[24:25], 0, s[12:13]
	v_add_f32_dpp v36, v36, v36 row_half_mirror row_mask:0xf bank_mask:0xf bound_ctrl:1
	v_lshl_add_u64 v[26:27], v[26:27], 0, s[12:13]
	v_lshl_add_u64 v[28:29], v[28:29], 0, s[14:15]
	v_add_f32_dpp v36, v36, v36 row_mirror row_mask:0xf bank_mask:0xf bound_ctrl:1
	v_mov_b32_e32 v37, v36
	s_nop 1
	v_permlane16_swap_b32_e32 v36, v37
	v_add_f32_e32 v36, v36, v37
	v_mov_b32_e32 v37, v36
	s_nop 1
	v_permlane32_swap_b32_e32 v36, v37
	v_add_f32_e32 v36, v36, v37
	v_fmamk_f32 v36, v36, 0x3a800000, v17
	v_mul_f32_e32 v37, 0x4b800000, v36
	v_cmp_gt_f32_e32 vcc, s22, v36
	s_waitcnt vmcnt(0)
	v_pk_mul_f32 v[14:15], v[14:15], v[42:43]
	v_cndmask_b32_e32 v36, v36, v37, vcc
	v_rsq_f32_e32 v36, v36
	v_pk_mul_f32 v[12:13], v[12:13], v[40:41]
	v_mul_f32_e32 v37, 0x45800000, v36
	v_cndmask_b32_e32 v36, v36, v37, vcc
	v_pk_mul_f32 v[14:15], v[14:15], v[36:37] op_sel_hi:[1,0]
	v_pk_mul_f32 v[12:13], v[12:13], v[36:37] op_sel_hi:[1,0]
	v_cmp_lt_i32_e32 vcc, s24, v16
	v_cvt_pk_bf16_f32 v12, v12, v13
	v_cvt_pk_bf16_f32 v13, v14, v15
	flat_store_dwordx2 v[34:35], v[12:13]
	s_or_b64 s[10:11], vcc, s[10:11]
	v_pk_mul_f32 v[10:11], v[10:11], v[46:47]
	v_pk_mul_f32 v[8:9], v[8:9], v[44:45]
	v_pk_mul_f32 v[10:11], v[10:11], v[36:37] op_sel_hi:[1,0]
	v_pk_mul_f32 v[8:9], v[8:9], v[36:37] op_sel_hi:[1,0]
	s_nop 0
	v_cvt_pk_bf16_f32 v8, v8, v9
	v_cvt_pk_bf16_f32 v9, v10, v11
	flat_store_dwordx2 v[34:35], v[8:9] offset:512
	v_pk_mul_f32 v[6:7], v[6:7], v[50:51]
	v_pk_mul_f32 v[4:5], v[4:5], v[48:49]
	v_pk_mul_f32 v[6:7], v[6:7], v[36:37] op_sel_hi:[1,0]
	v_pk_mul_f32 v[4:5], v[4:5], v[36:37] op_sel_hi:[1,0]
	s_nop 0
	v_cvt_pk_bf16_f32 v4, v4, v5
	v_cvt_pk_bf16_f32 v5, v6, v7
	flat_store_dwordx2 v[34:35], v[4:5] offset:1024
	v_pk_mul_f32 v[2:3], v[2:3], v[54:55]
	v_pk_mul_f32 v[0:1], v[0:1], v[52:53]
	v_pk_mul_f32 v[2:3], v[2:3], v[36:37] op_sel_hi:[1,0]
	v_pk_mul_f32 v[0:1], v[0:1], v[36:37] op_sel_hi:[1,0]
	s_nop 0
	v_cvt_pk_bf16_f32 v0, v0, v1
	v_cvt_pk_bf16_f32 v1, v2, v3
	flat_store_dwordx2 v[34:35], v[0:1] offset:1536
	s_andn2_b64 exec, exec, s[10:11]
	s_cbranch_execz .LBB0_523
.LBB0_521:
	v_lshl_add_u64 v[0:1], v[26:27], 0, v[18:19]
	v_add_co_u32_e32 v0, vcc, 0xa800000, v0
	v_lshl_add_u64 v[42:43], s[8:9], 0, v[28:29]
	s_nop 0
	v_addc_co_u32_e32 v1, vcc, 0, v1, vcc
	flat_load_dwordx2 v[46:47], v[0:1]
	flat_load_dwordx2 v[48:49], v[0:1] offset:512
	flat_load_dwordx2 v[50:51], v[0:1] offset:1024
	flat_load_dwordx2 v[52:53], v[0:1] offset:1536
	s_nop 0
	global_load_dwordx4 v[0:3], v[20:21], off
	global_load_dwordx4 v[4:7], v[20:21], off offset:1024
	global_load_dwordx4 v[8:11], v[20:21], off offset:2048
	global_load_dwordx4 v[12:15], v[20:21], off offset:3072
	global_load_dwordx4 v[30:33], v[42:43], off
	global_load_dwordx4 v[34:37], v[42:43], off offset:1024
	global_load_dwordx4 v[38:41], v[42:43], off offset:2048
	s_nop 0
	global_load_dwordx4 v[42:45], v[42:43], off offset:3072
	s_and_b64 vcc, exec, s[2:3]
	s_waitcnt vmcnt(0) lgkmcnt(0)
	v_and_b32_e32 v55, 0xffff0000, v46
	v_and_b32_e32 v57, 0xffff0000, v48
	v_lshlrev_b32_e32 v54, 16, v46
	v_lshlrev_b32_e32 v56, 16, v48
	v_and_b32_e32 v59, 0xffff0000, v50
	v_mul_f32_e32 v64, v55, v55
	v_mul_f32_e32 v65, v57, v57
	v_lshlrev_b32_e32 v46, 16, v47
	v_lshlrev_b32_e32 v48, 16, v49
	v_lshlrev_b32_e32 v58, 16, v50
	v_and_b32_e32 v61, 0xffff0000, v52
	v_mul_f32_e32 v66, v59, v59
	v_fmac_f32_e32 v64, v54, v54
	v_fmac_f32_e32 v65, v56, v56
	v_and_b32_e32 v47, 0xffff0000, v47
	v_and_b32_e32 v49, 0xffff0000, v49
	v_lshlrev_b32_e32 v50, 16, v51
	v_lshlrev_b32_e32 v60, 16, v52
	v_mul_f32_e32 v67, v61, v61
	v_fmac_f32_e32 v66, v58, v58
	v_fmac_f32_e32 v64, v46, v46
	v_fmac_f32_e32 v65, v48, v48
	v_and_b32_e32 v51, 0xffff0000, v51
	v_lshlrev_b32_e32 v52, 16, v53
	v_fmac_f32_e32 v67, v60, v60
	v_fmac_f32_e32 v66, v50, v50
	v_fmac_f32_e32 v64, v47, v47
	v_fmac_f32_e32 v65, v49, v49
	v_and_b32_e32 v53, 0xffff0000, v53
	v_pk_mul_f32 v[62:63], v[58:59], v[8:9]
	v_fmac_f32_e32 v67, v52, v52
	v_fmac_f32_e32 v66, v51, v51
	v_add_f32_e32 v8, v64, v65
	v_fmac_f32_e32 v67, v53, v53
	v_add_f32_e32 v8, v8, v66
	v_add_f32_e32 v8, v8, v67
	v_pk_mul_f32 v[0:1], v[54:55], v[0:1]
	v_pk_mul_f32 v[2:3], v[46:47], v[2:3]
	v_add_f32_dpp v8, v8, v8 quad_perm:[1,0,3,2] row_mask:0xf bank_mask:0xf bound_ctrl:1
	v_pk_mul_f32 v[4:5], v[56:57], v[4:5]
	v_pk_mul_f32 v[6:7], v[48:49], v[6:7]
	v_add_f32_dpp v8, v8, v8 quad_perm:[2,3,0,1] row_mask:0xf bank_mask:0xf bound_ctrl:1
	v_pk_mul_f32 v[46:47], v[50:51], v[10:11]
	v_pk_mul_f32 v[48:49], v[60:61], v[12:13]
	v_add_f32_dpp v8, v8, v8 row_half_mirror row_mask:0xf bank_mask:0xf bound_ctrl:1
	v_pk_mul_f32 v[50:51], v[52:53], v[14:15]
	s_nop 0
	v_add_f32_dpp v8, v8, v8 row_mirror row_mask:0xf bank_mask:0xf bound_ctrl:1
	v_mov_b32_e32 v9, v8
	s_nop 1
	v_permlane16_swap_b32_e32 v8, v9
	v_add_f32_e32 v8, v8, v9
	v_mov_b32_e32 v9, v8
	s_nop 1
	v_permlane32_swap_b32_e32 v8, v9
	v_add_f32_e32 v8, v8, v9
	v_fmamk_f32 v8, v8, 0x3a800000, v17
	v_mul_f32_e32 v9, 0x4b800000, v8
	v_cmp_gt_f32_e64 s[4:5], s22, v8
	s_nop 1
	v_cndmask_b32_e64 v8, v8, v9, s[4:5]
	v_rsq_f32_e32 v8, v8
	s_nop 0
	v_mul_f32_e32 v9, 0x45800000, v8
	v_cndmask_b32_e64 v8, v8, v9, s[4:5]
	v_mul_f32_e32 v52, 0.5, v8
	v_pk_fma_f32 v[14:15], v[2:3], v[52:53], v[32:33] op_sel_hi:[1,0,1]
	v_pk_fma_f32 v[12:13], v[0:1], v[52:53], v[30:31] op_sel_hi:[1,0,1]
	v_pk_fma_f32 v[10:11], v[6:7], v[52:53], v[36:37] op_sel_hi:[1,0,1]
	v_pk_fma_f32 v[8:9], v[4:5], v[52:53], v[34:35] op_sel_hi:[1,0,1]
	v_pk_fma_f32 v[6:7], v[46:47], v[52:53], v[40:41] op_sel_hi:[1,0,1]
	v_pk_fma_f32 v[4:5], v[62:63], v[52:53], v[38:39] op_sel_hi:[1,0,1]
	v_pk_fma_f32 v[2:3], v[50:51], v[52:53], v[44:45] op_sel_hi:[1,0,1]
	v_pk_fma_f32 v[0:1], v[48:49], v[52:53], v[42:43] op_sel_hi:[1,0,1]
	global_load_dwordx4 v[40:43], v[22:23], off
	global_load_dwordx4 v[44:47], v[22:23], off offset:1024
	global_load_dwordx4 v[48:51], v[22:23], off offset:2048
	global_load_dwordx4 v[52:55], v[22:23], off offset:3072
	s_cbranch_vccnz .LBB0_520
	s_load_dwordx4 s[28:31], s[0:1], 0x140
	s_waitcnt lgkmcnt(0)
	v_lshl_add_u64 v[30:31], s[28:29], 0, v[28:29]
	global_store_dwordx4 v[30:31], v[12:15], off sc0 sc1
	s_nop 1
	v_lshl_add_u64 v[32:33], v[30:31], 0, s[16:17]
	global_store_dwordx4 v[32:33], v[8:11], off sc0 sc1
	s_nop 1
	v_lshl_add_u64 v[34:35], v[30:31], 0, s[18:19]
	global_store_dwordx4 v[34:35], v[4:7], off sc0 sc1
	s_nop 1
	v_lshl_add_u64 v[36:37], v[30:31], 0, s[20:21]
	global_store_dwordx4 v[36:37], v[0:3], off sc0 sc1
	s_nop 1
	s_branch .LBB0_520

.LBB0_1831:
	v_mul_f32_e32 v36, v13, v13
	v_mul_f32_e32 v37, v9, v9
	v_mul_f32_e32 v38, v5, v5
	v_fmac_f32_e32 v36, v12, v12
	v_fmac_f32_e32 v37, v8, v8
	v_mul_f32_e32 v39, v1, v1
	v_fmac_f32_e32 v38, v4, v4
	v_fmac_f32_e32 v36, v14, v14
	v_fmac_f32_e32 v37, v10, v10
	v_fmac_f32_e32 v39, v0, v0
	v_fmac_f32_e32 v38, v6, v6
	v_fmac_f32_e32 v36, v15, v15
	v_fmac_f32_e32 v37, v11, v11
	v_fmac_f32_e32 v39, v2, v2
	v_fmac_f32_e32 v38, v7, v7
	v_add_f32_e32 v36, v36, v37
	v_fmac_f32_e32 v39, v3, v3
	v_add_f32_e32 v36, v38, v36
	v_add_f32_e32 v36, v39, v36
	v_lshl_add_u64 v[34:35], v[24:25], 0, v[18:19]
	v_add_co_u32_e64 v34, s[4:5], s21, v34
	v_add_f32_dpp v36, v36, v36 quad_perm:[1,0,3,2] row_mask:0xf bank_mask:0xf bound_ctrl:1
	s_nop 0
	v_addc_co_u32_e64 v35, s[4:5], 0, v35, s[4:5]
	v_add_f32_dpp v36, v36, v36 quad_perm:[2,3,0,1] row_mask:0xf bank_mask:0xf bound_ctrl:1
	v_add_u32_e32 v16, s56, v16
	v_lshl_add_u64 v[24:25], v[24:25], 0, s[10:11]
	v_add_f32_dpp v36, v36, v36 row_half_mirror row_mask:0xf bank_mask:0xf bound_ctrl:1
	v_lshl_add_u64 v[26:27], v[26:27], 0, s[10:11]
	v_lshl_add_u64 v[28:29], v[28:29], 0, s[12:13]
	v_add_f32_dpp v36, v36, v36 row_mirror row_mask:0xf bank_mask:0xf bound_ctrl:1
	v_mov_b32_e32 v37, v36
	s_nop 1
	v_permlane16_swap_b32_e32 v36, v37
	v_add_f32_e32 v36, v36, v37
	v_mov_b32_e32 v37, v36
	s_nop 1
	v_permlane32_swap_b32_e32 v36, v37
	v_add_f32_e32 v36, v36, v37
	v_fmamk_f32 v36, v36, 0x3a800000, v17
	v_mul_f32_e32 v37, 0x4b800000, v36
	v_cmp_gt_f32_e32 vcc, s20, v36
	s_waitcnt vmcnt(0)
	v_pk_mul_f32 v[14:15], v[14:15], v[42:43]
	v_cndmask_b32_e32 v36, v36, v37, vcc
	v_rsq_f32_e32 v36, v36
	v_pk_mul_f32 v[12:13], v[12:13], v[40:41]
	v_mul_f32_e32 v37, 0x45800000, v36
	v_cndmask_b32_e32 v36, v36, v37, vcc
	v_pk_mul_f32 v[14:15], v[14:15], v[36:37] op_sel_hi:[1,0]
	v_pk_mul_f32 v[12:13], v[12:13], v[36:37] op_sel_hi:[1,0]
	v_cmp_lt_i32_e32 vcc, s22, v16
	v_cvt_pk_bf16_f32 v12, v12, v13
	v_cvt_pk_bf16_f32 v13, v14, v15
	flat_store_dwordx2 v[34:35], v[12:13]
	s_or_b64 s[8:9], vcc, s[8:9]
	v_pk_mul_f32 v[10:11], v[10:11], v[46:47]
	v_pk_mul_f32 v[8:9], v[8:9], v[44:45]
	v_pk_mul_f32 v[10:11], v[10:11], v[36:37] op_sel_hi:[1,0]
	v_pk_mul_f32 v[8:9], v[8:9], v[36:37] op_sel_hi:[1,0]
	s_nop 0
	v_cvt_pk_bf16_f32 v8, v8, v9
	v_cvt_pk_bf16_f32 v9, v10, v11
	flat_store_dwordx2 v[34:35], v[8:9] offset:512
	v_pk_mul_f32 v[6:7], v[6:7], v[50:51]
	v_pk_mul_f32 v[4:5], v[4:5], v[48:49]
	v_pk_mul_f32 v[6:7], v[6:7], v[36:37] op_sel_hi:[1,0]
	v_pk_mul_f32 v[4:5], v[4:5], v[36:37] op_sel_hi:[1,0]
	s_nop 0
	v_cvt_pk_bf16_f32 v4, v4, v5
	v_cvt_pk_bf16_f32 v5, v6, v7
	flat_store_dwordx2 v[34:35], v[4:5] offset:1024
	v_pk_mul_f32 v[2:3], v[2:3], v[54:55]
	v_pk_mul_f32 v[0:1], v[0:1], v[52:53]
	v_pk_mul_f32 v[2:3], v[2:3], v[36:37] op_sel_hi:[1,0]
	v_pk_mul_f32 v[0:1], v[0:1], v[36:37] op_sel_hi:[1,0]
	s_nop 0
	v_cvt_pk_bf16_f32 v0, v0, v1
	v_cvt_pk_bf16_f32 v1, v2, v3
	flat_store_dwordx2 v[34:35], v[0:1] offset:1536
	s_andn2_b64 exec, exec, s[8:9]
	s_cbranch_execz .LBB0_1834
; DI float bflo(unsigned u) { return __uint_as_float(u << 16); }
; DI float bfhi(unsigned u) { return __uint_as_float(u & 0xffff0000u); }
; DI void st16_wt(void* p, u32x4 v) { asm volatile("global_store_dwordx4 %0, %1, off sc0 sc1\n\ts_nop 1" :: "v"(p), "v"(v) : "memory"); }
; DI void row_phase(int wv, int mode, const float* X, const bf16_t* Y, const float* ga, float coef, const float* gb, float* Xout, bf16_t* A, int a_pad) {
;     ...
;         for (int j = 0; j < 4; ++j) v[j] = *(const f32x4*)(X + (size_t)r * DM + 4 * lane + 256 * j);
;         if (mode == 1) { f32x4 y[4]; float s = 0.f;
; #pragma unroll
;             for (int j = 0; j < 4; ++j) { const u32x2 yv = *(const u32x2*)(Y + (size_t)r * DM + 4 * lane + 256 * j); y[j] = (f32x4){bflo(yv.x), bfhi(yv.x), bflo(yv.y), bfhi(yv.y)}; s += y[j][0] * y[j][0] + y[j][1] * y[j][1] + y[j][2] * y[j][2] + y[j][3] * y[j][3]; }
;             const float rs = coef * rsqrtf(wave_sum(s) * (1.f / DM) + 1e-6f);
; #pragma unroll
;             for (int j = 0; j < 4; ++j) { const f32x4 gg = *(const f32x4*)(ga + 4 * lane + 256 * j); v[j] += y[j] * gg * rs; } }
;         if (Xout) {
; #pragma unroll
;             for (int j = 0; j < 4; ++j) st16_wt(Xout + (size_t)r * DM + 4 * lane + 256 * j, __builtin_bit_cast(u32x4, v[j])); }
;         if (gb) { float s = 0.f;
; #pragma unroll
;             for (int j = 0; j < 4; ++j) s += v[j][0] * v[j][0] + v[j][1] * v[j][1] + v[j][2] * v[j][2] + v[j][3] * v[j][3];
;             const float rs = rsqrtf(wave_sum(s) * (1.f / DM) + 1e-6f);
;             const size_t ar = a_pad ? (size_t)(r + (r >> 13) + 1) : (size_t)r;
; #pragma unroll
;             for (int j = 0; j < 4; ++j) { const f32x4 gg = *(const f32x4*)(gb + 4 * lane + 256 * j); const f32x4 o = v[j] * gg * rs;
.LBB0_1832:
	v_lshl_add_u64 v[0:1], v[26:27], 0, v[18:19]
	v_add_co_u32_e32 v0, vcc, 0x5000000, v0
	s_nop 1
	v_addc_co_u32_e32 v1, vcc, 0, v1, vcc
	flat_load_dwordx2 v[46:47], v[0:1]
	flat_load_dwordx2 v[48:49], v[0:1] offset:512
	flat_load_dwordx2 v[50:51], v[0:1] offset:1024
	flat_load_dwordx2 v[52:53], v[0:1] offset:1536
	s_nop 0
	global_load_dwordx4 v[0:3], v[20:21], off
	global_load_dwordx4 v[4:7], v[20:21], off offset:1024
	global_load_dwordx4 v[8:11], v[20:21], off offset:2048
	global_load_dwordx4 v[12:15], v[20:21], off offset:3072
	global_load_dwordx4 v[30:33], v[28:29], off
	global_load_dwordx4 v[34:37], v[28:29], off offset:1024
	global_load_dwordx4 v[38:41], v[28:29], off offset:2048
	global_load_dwordx4 v[42:45], v[28:29], off offset:3072
	s_and_b64 vcc, exec, s[2:3]
	s_waitcnt vmcnt(0) lgkmcnt(0)
	v_and_b32_e32 v55, 0xffff0000, v46
	v_and_b32_e32 v57, 0xffff0000, v48
	v_lshlrev_b32_e32 v54, 16, v46
	v_lshlrev_b32_e32 v56, 16, v48
	v_and_b32_e32 v59, 0xffff0000, v50
	v_mul_f32_e32 v64, v55, v55
	v_mul_f32_e32 v65, v57, v57
	v_lshlrev_b32_e32 v46, 16, v47
	v_lshlrev_b32_e32 v48, 16, v49
	v_lshlrev_b32_e32 v58, 16, v50
	v_and_b32_e32 v61, 0xffff0000, v52
	v_mul_f32_e32 v66, v59, v59
	v_fmac_f32_e32 v64, v54, v54
	v_fmac_f32_e32 v65, v56, v56
	v_and_b32_e32 v47, 0xffff0000, v47
	v_and_b32_e32 v49, 0xffff0000, v49
	v_lshlrev_b32_e32 v50, 16, v51
	v_lshlrev_b32_e32 v60, 16, v52
	v_mul_f32_e32 v67, v61, v61
	v_fmac_f32_e32 v66, v58, v58
	v_fmac_f32_e32 v64, v46, v46
	v_fmac_f32_e32 v65, v48, v48
	v_and_b32_e32 v51, 0xffff0000, v51
	v_lshlrev_b32_e32 v52, 16, v53
	v_fmac_f32_e32 v67, v60, v60
	v_fmac_f32_e32 v66, v50, v50
	v_fmac_f32_e32 v64, v47, v47
	v_fmac_f32_e32 v65, v49, v49
	v_and_b32_e32 v53, 0xffff0000, v53
	v_pk_mul_f32 v[62:63], v[58:59], v[8:9]
	v_fmac_f32_e32 v67, v52, v52
	v_fmac_f32_e32 v66, v51, v51
	v_add_f32_e32 v8, v64, v65
	v_fmac_f32_e32 v67, v53, v53
	v_add_f32_e32 v8, v8, v66
	v_add_f32_e32 v8, v8, v67
	v_pk_mul_f32 v[0:1], v[54:55], v[0:1]
	v_pk_mul_f32 v[2:3], v[46:47], v[2:3]
	v_add_f32_dpp v8, v8, v8 quad_perm:[1,0,3,2] row_mask:0xf bank_mask:0xf bound_ctrl:1
	v_pk_mul_f32 v[4:5], v[56:57], v[4:5]
	v_pk_mul_f32 v[6:7], v[48:49], v[6:7]
	v_add_f32_dpp v8, v8, v8 quad_perm:[2,3,0,1] row_mask:0xf bank_mask:0xf bound_ctrl:1
	v_pk_mul_f32 v[46:47], v[50:51], v[10:11]
	v_pk_mul_f32 v[48:49], v[60:61], v[12:13]
	v_add_f32_dpp v8, v8, v8 row_half_mirror row_mask:0xf bank_mask:0xf bound_ctrl:1
	v_pk_mul_f32 v[50:51], v[52:53], v[14:15]
	s_nop 0
	v_add_f32_dpp v8, v8, v8 row_mirror row_mask:0xf bank_mask:0xf bound_ctrl:1
	v_mov_b32_e32 v9, v8
	s_nop 1
	v_permlane16_swap_b32_e32 v8, v9
	v_add_f32_e32 v8, v8, v9
	v_mov_b32_e32 v9, v8
	s_nop 1
	v_permlane32_swap_b32_e32 v8, v9
	v_add_f32_e32 v8, v8, v9
	v_fmamk_f32 v8, v8, 0x3a800000, v17
	v_mul_f32_e32 v9, 0x4b800000, v8
	v_cmp_gt_f32_e64 s[4:5], s20, v8
	s_nop 1
	v_cndmask_b32_e64 v8, v8, v9, s[4:5]
	v_rsq_f32_e32 v8, v8
	s_nop 0
	v_mul_f32_e32 v9, 0x45800000, v8
	v_cndmask_b32_e64 v52, v8, v9, s[4:5]
	v_pk_fma_f32 v[14:15], v[2:3], v[52:53], v[32:33] op_sel_hi:[1,0,1]
	v_pk_fma_f32 v[12:13], v[0:1], v[52:53], v[30:31] op_sel_hi:[1,0,1]
	v_pk_fma_f32 v[10:11], v[6:7], v[52:53], v[36:37] op_sel_hi:[1,0,1]
	v_pk_fma_f32 v[8:9], v[4:5], v[52:53], v[34:35] op_sel_hi:[1,0,1]
	v_pk_fma_f32 v[6:7], v[46:47], v[52:53], v[40:41] op_sel_hi:[1,0,1]
	v_pk_fma_f32 v[4:5], v[62:63], v[52:53], v[38:39] op_sel_hi:[1,0,1]
	v_pk_fma_f32 v[2:3], v[50:51], v[52:53], v[44:45] op_sel_hi:[1,0,1]
	v_pk_fma_f32 v[0:1], v[48:49], v[52:53], v[42:43] op_sel_hi:[1,0,1]
	global_load_dwordx4 v[40:43], v[22:23], off
	global_load_dwordx4 v[44:47], v[22:23], off offset:1024
	global_load_dwordx4 v[48:51], v[22:23], off offset:2048
	global_load_dwordx4 v[52:55], v[22:23], off offset:3072
	s_cbranch_vccnz .LBB0_1831
	global_store_dwordx4 v[28:29], v[12:15], off sc0 sc1
	s_nop 1
	v_lshl_add_u64 v[30:31], v[28:29], 0, s[14:15]
	global_store_dwordx4 v[30:31], v[8:11], off sc0 sc1
	s_nop 1
	v_lshl_add_u64 v[32:33], v[28:29], 0, s[16:17]
	global_store_dwordx4 v[32:33], v[4:7], off sc0 sc1
	s_nop 1
	v_lshl_add_u64 v[34:35], v[28:29], 0, s[18:19]
	global_store_dwordx4 v[34:35], v[0:3], off sc0 sc1
	s_nop 1
	s_branch .LBB0_1831

; DI float bflo(unsigned u) { return __uint_as_float(u << 16); }
; DI float bfhi(unsigned u) { return __uint_as_float(u & 0xffff0000u); }
; DI void st16_wt(void* p, u32x4 v) { asm volatile("global_store_dwordx4 %0, %1, off sc0 sc1\n\ts_nop 1" :: "v"(p), "v"(v) : "memory"); }
; DI void row_phase(int wv, int mode, const float* X, const bf16_t* Y, const float* ga, float coef, const float* gb, float* Xout, bf16_t* A, int a_pad) {
;     ...
;         for (int j = 0; j < 4; ++j) v[j] = *(const f32x4*)(X + (size_t)r * DM + 4 * lane + 256 * j);
;         if (mode == 1) { f32x4 y[4]; float s = 0.f;
; #pragma unroll
;             for (int j = 0; j < 4; ++j) { const u32x2 yv = *(const u32x2*)(Y + (size_t)r * DM + 4 * lane + 256 * j); y[j] = (f32x4){bflo(yv.x), bfhi(yv.x), bflo(yv.y), bfhi(yv.y)}; s += y[j][0] * y[j][0] + y[j][1] * y[j][1] + y[j][2] * y[j][2] + y[j][3] * y[j][3]; }
;             const float rs = coef * rsqrtf(wave_sum(s) * (1.f / DM) + 1e-6f);
; #pragma unroll
;             for (int j = 0; j < 4; ++j) { const f32x4 gg = *(const f32x4*)(ga + 4 * lane + 256 * j); v[j] += y[j] * gg * rs; } }
;         if (Xout) {
; #pragma unroll
;             for (int j = 0; j < 4; ++j) st16_wt(Xout + (size_t)r * DM + 4 * lane + 256 * j, __builtin_bit_cast(u32x4, v[j])); }
;         if (gb) { float s = 0.f;
; #pragma unroll
;             for (int j = 0; j < 4; ++j) s += v[j][0] * v[j][0] + v[j][1] * v[j][1] + v[j][2] * v[j][2] + v[j][3] * v[j][3];
;             const float rs = rsqrtf(wave_sum(s) * (1.f / DM) + 1e-6f);
;             const size_t ar = a_pad ? (size_t)(r + (r >> 13) + 1) : (size_t)r;
; #pragma unroll
;             for (int j = 0; j < 4; ++j) { const f32x4 gg = *(const f32x4*)(gb + 4 * lane + 256 * j); const f32x4 o = v[j] * gg * rs;
.LBB0_2032:
	v_lshl_add_u64 v[0:1], v[26:27], 0, v[18:19]
	v_add_co_u32_e32 v0, vcc, 0xa800000, v0
	s_nop 1
	v_addc_co_u32_e32 v1, vcc, 0, v1, vcc
	flat_load_dwordx2 v[46:47], v[0:1]
	flat_load_dwordx2 v[48:49], v[0:1] offset:512
	flat_load_dwordx2 v[50:51], v[0:1] offset:1024
	flat_load_dwordx2 v[52:53], v[0:1] offset:1536
	s_nop 0
	global_load_dwordx4 v[0:3], v[20:21], off
	global_load_dwordx4 v[4:7], v[20:21], off offset:1024
	global_load_dwordx4 v[8:11], v[20:21], off offset:2048
	global_load_dwordx4 v[12:15], v[20:21], off offset:3072
	global_load_dwordx4 v[30:33], v[28:29], off
	global_load_dwordx4 v[34:37], v[28:29], off offset:1024
	global_load_dwordx4 v[38:41], v[28:29], off offset:2048
	global_load_dwordx4 v[42:45], v[28:29], off offset:3072
	s_and_b64 vcc, exec, s[2:3]
	s_waitcnt vmcnt(0) lgkmcnt(0)
	v_and_b32_e32 v55, 0xffff0000, v46
	v_and_b32_e32 v57, 0xffff0000, v48
	v_lshlrev_b32_e32 v54, 16, v46
	v_lshlrev_b32_e32 v56, 16, v48
	v_and_b32_e32 v59, 0xffff0000, v50
	v_mul_f32_e32 v64, v55, v55
	v_mul_f32_e32 v65, v57, v57
	v_lshlrev_b32_e32 v46, 16, v47
	v_lshlrev_b32_e32 v48, 16, v49
	v_lshlrev_b32_e32 v58, 16, v50
	v_and_b32_e32 v61, 0xffff0000, v52
	v_mul_f32_e32 v66, v59, v59
	v_fmac_f32_e32 v64, v54, v54
	v_fmac_f32_e32 v65, v56, v56
	v_and_b32_e32 v47, 0xffff0000, v47
	v_and_b32_e32 v49, 0xffff0000, v49
	v_lshlrev_b32_e32 v50, 16, v51
	v_lshlrev_b32_e32 v60, 16, v52
	v_mul_f32_e32 v67, v61, v61
	v_fmac_f32_e32 v66, v58, v58
	v_fmac_f32_e32 v64, v46, v46
	v_fmac_f32_e32 v65, v48, v48
	v_and_b32_e32 v51, 0xffff0000, v51
	v_lshlrev_b32_e32 v52, 16, v53
	v_fmac_f32_e32 v67, v60, v60
	v_fmac_f32_e32 v66, v50, v50
	v_fmac_f32_e32 v64, v47, v47
	v_fmac_f32_e32 v65, v49, v49
	v_and_b32_e32 v53, 0xffff0000, v53
	v_pk_mul_f32 v[62:63], v[58:59], v[8:9]
	v_fmac_f32_e32 v67, v52, v52
	v_fmac_f32_e32 v66, v51, v51
	v_add_f32_e32 v8, v64, v65
	v_fmac_f32_e32 v67, v53, v53
	v_add_f32_e32 v8, v8, v66
	v_add_f32_e32 v8, v8, v67
	v_pk_mul_f32 v[0:1], v[54:55], v[0:1]
	v_pk_mul_f32 v[2:3], v[46:47], v[2:3]
	v_add_f32_dpp v8, v8, v8 quad_perm:[1,0,3,2] row_mask:0xf bank_mask:0xf bound_ctrl:1
	v_pk_mul_f32 v[4:5], v[56:57], v[4:5]
	v_pk_mul_f32 v[6:7], v[48:49], v[6:7]
	v_add_f32_dpp v8, v8, v8 quad_perm:[2,3,0,1] row_mask:0xf bank_mask:0xf bound_ctrl:1
	v_pk_mul_f32 v[46:47], v[50:51], v[10:11]
	v_pk_mul_f32 v[48:49], v[60:61], v[12:13]
	v_add_f32_dpp v8, v8, v8 row_half_mirror row_mask:0xf bank_mask:0xf bound_ctrl:1
	v_pk_mul_f32 v[50:51], v[52:53], v[14:15]
	s_nop 0
	v_add_f32_dpp v8, v8, v8 row_mirror row_mask:0xf bank_mask:0xf bound_ctrl:1
	v_mov_b32_e32 v9, v8
	s_nop 1
	v_permlane16_swap_b32_e32 v8, v9
	v_add_f32_e32 v8, v8, v9
	v_mov_b32_e32 v9, v8
	s_nop 1
	v_permlane32_swap_b32_e32 v8, v9
	v_add_f32_e32 v8, v8, v9
	v_fmamk_f32 v8, v8, 0x3a800000, v17
	v_mul_f32_e32 v9, 0x4b800000, v8
	v_cmp_gt_f32_e64 s[4:5], s20, v8
	s_nop 1
	v_cndmask_b32_e64 v8, v8, v9, s[4:5]
	v_rsq_f32_e32 v8, v8
	s_nop 0
	v_mul_f32_e32 v9, 0x45800000, v8
	v_cndmask_b32_e64 v8, v8, v9, s[4:5]
	v_mul_f32_e32 v52, 0.5, v8
	v_pk_fma_f32 v[14:15], v[2:3], v[52:53], v[32:33] op_sel_hi:[1,0,1]
	v_pk_fma_f32 v[12:13], v[0:1], v[52:53], v[30:31] op_sel_hi:[1,0,1]
	v_pk_fma_f32 v[10:11], v[6:7], v[52:53], v[36:37] op_sel_hi:[1,0,1]
	v_pk_fma_f32 v[8:9], v[4:5], v[52:53], v[34:35] op_sel_hi:[1,0,1]
	v_pk_fma_f32 v[6:7], v[46:47], v[52:53], v[40:41] op_sel_hi:[1,0,1]
	v_pk_fma_f32 v[4:5], v[62:63], v[52:53], v[38:39] op_sel_hi:[1,0,1]
	v_pk_fma_f32 v[2:3], v[50:51], v[52:53], v[44:45] op_sel_hi:[1,0,1]
	v_pk_fma_f32 v[0:1], v[48:49], v[52:53], v[42:43] op_sel_hi:[1,0,1]
	global_load_dwordx4 v[40:43], v[22:23], off
	global_load_dwordx4 v[44:47], v[22:23], off offset:1024
	global_load_dwordx4 v[48:51], v[22:23], off offset:2048
	global_load_dwordx4 v[52:55], v[22:23], off offset:3072
	s_cbranch_vccnz .LBB0_2031
	global_store_dwordx4 v[28:29], v[12:15], off sc0 sc1
	s_nop 1
	v_lshl_add_u64 v[30:31], v[28:29], 0, s[14:15]
	global_store_dwordx4 v[30:31], v[8:11], off sc0 sc1
	s_nop 1
	v_lshl_add_u64 v[32:33], v[28:29], 0, s[16:17]
	global_store_dwordx4 v[32:33], v[4:7], off sc0 sc1
	s_nop 1
	v_lshl_add_u64 v[34:35], v[28:29], 0, s[18:19]
	global_store_dwordx4 v[34:35], v[0:3], off sc0 sc1
	s_nop 1
	s_branch .LBB0_2031

; DI unsigned pk2(float lo, float hi) { f32x2 v = {lo, hi}; bf16x2_t b = __builtin_convertvector(v, bf16x2_t); return __builtin_bit_cast(unsigned, b); }
; DI void row_phase(int wv, int mode, const float* X, const bf16_t* Y, const float* ga, float coef, const float* gb, float* Xout, bf16_t* A, int a_pad) {
;     ...
;         if (gb) { float s = 0.f;
; #pragma unroll
;             for (int j = 0; j < 4; ++j) s += v[j][0] * v[j][0] + v[j][1] * v[j][1] + v[j][2] * v[j][2] + v[j][3] * v[j][3];
;             const float rs = rsqrtf(wave_sum(s) * (1.f / DM) + 1e-6f);
;             const size_t ar = a_pad ? (size_t)(r + (r >> 13) + 1) : (size_t)r;
; #pragma unroll
;             for (int j = 0; j < 4; ++j) { const f32x4 gg = *(const f32x4*)(gb + 4 * lane + 256 * j); const f32x4 o = v[j] * gg * rs;
;                 u32x2 w; w.x = pk2(o[0], o[1]); w.y = pk2(o[2], o[3]); *(u32x2*)(A + ar * DM + 4 * lane + 256 * j) = w; } }
.LBB0_2524:
	v_mul_f32_e32 v29, v13, v13
	v_mul_f32_e32 v35, v9, v9
	v_mul_f32_e32 v36, v5, v5
	v_fmac_f32_e32 v29, v12, v12
	v_fmac_f32_e32 v35, v8, v8
	v_mul_f32_e32 v37, v1, v1
	v_fmac_f32_e32 v36, v4, v4
	v_fmac_f32_e32 v29, v14, v14
	v_fmac_f32_e32 v35, v10, v10
	v_fmac_f32_e32 v37, v0, v0
	v_fmac_f32_e32 v36, v6, v6
	v_fmac_f32_e32 v29, v15, v15
	v_fmac_f32_e32 v35, v11, v11
	v_fmac_f32_e32 v37, v2, v2
	v_fmac_f32_e32 v36, v7, v7
	v_add_f32_e32 v29, v29, v35
	v_fmac_f32_e32 v37, v3, v3
	v_add_f32_e32 v29, v36, v29
	v_add_f32_e32 v29, v37, v29
	v_ashrrev_i32_e32 v34, 13, v16
	v_add3_u32 v34, v16, v34, 1
	v_add_f32_dpp v29, v29, v29 quad_perm:[1,0,3,2] row_mask:0xf bank_mask:0xf bound_ctrl:1
	v_add_u32_e32 v16, s56, v16
	v_lshl_add_u64 v[24:25], v[24:25], 0, s[12:13]
	v_add_f32_dpp v29, v29, v29 quad_perm:[2,3,0,1] row_mask:0xf bank_mask:0xf bound_ctrl:1
	v_lshl_add_u64 v[26:27], v[26:27], 0, s[14:15]
	s_waitcnt vmcnt(0)
	v_pk_mul_f32 v[14:15], v[14:15], v[42:43]
	v_add_f32_dpp v29, v29, v29 row_half_mirror row_mask:0xf bank_mask:0xf bound_ctrl:1
	v_pk_mul_f32 v[12:13], v[12:13], v[40:41]
	s_nop 0
	v_add_f32_dpp v29, v29, v29 row_mirror row_mask:0xf bank_mask:0xf bound_ctrl:1
	v_mov_b32_e32 v35, v29
	s_nop 1
	v_permlane16_swap_b32_e32 v29, v35
	v_add_f32_e32 v29, v29, v35
	v_mov_b32_e32 v35, v29
	s_nop 1
	v_permlane32_swap_b32_e32 v29, v35
	v_add_f32_e32 v29, v29, v35
	v_fmamk_f32 v29, v29, 0x3a800000, v17
	v_mul_f32_e32 v35, 0x4b800000, v29
	v_cmp_gt_f32_e32 vcc, s22, v29
	s_nop 1
	v_cndmask_b32_e32 v29, v29, v35, vcc
	v_rsq_f32_e32 v29, v29
	v_ashrrev_i32_e32 v35, 31, v34
	v_lshlrev_b64 v[34:35], 11, v[34:35]
	v_lshl_add_u64 v[34:35], v[22:23], 0, v[34:35]
	v_mul_f32_e32 v36, 0x45800000, v29
	v_cndmask_b32_e32 v36, v29, v36, vcc
	v_pk_mul_f32 v[14:15], v[14:15], v[36:37] op_sel_hi:[1,0]
	v_pk_mul_f32 v[12:13], v[12:13], v[36:37] op_sel_hi:[1,0]
	v_cmp_lt_i32_e32 vcc, s23, v16
	v_cvt_pk_bf16_f32 v12, v12, v13
	v_cvt_pk_bf16_f32 v13, v14, v15
	flat_store_dwordx2 v[34:35], v[12:13]
	s_or_b64 s[8:9], vcc, s[8:9]
	v_pk_mul_f32 v[10:11], v[10:11], v[46:47]
	v_pk_mul_f32 v[8:9], v[8:9], v[44:45]
	v_pk_mul_f32 v[10:11], v[10:11], v[36:37] op_sel_hi:[1,0]
	v_pk_mul_f32 v[8:9], v[8:9], v[36:37] op_sel_hi:[1,0]
	s_nop 0
	v_cvt_pk_bf16_f32 v8, v8, v9
	v_cvt_pk_bf16_f32 v9, v10, v11
	flat_store_dwordx2 v[34:35], v[8:9] offset:512
	v_pk_mul_f32 v[6:7], v[6:7], v[50:51]
	v_pk_mul_f32 v[4:5], v[4:5], v[48:49]
	v_pk_mul_f32 v[6:7], v[6:7], v[36:37] op_sel_hi:[1,0]
	v_pk_mul_f32 v[4:5], v[4:5], v[36:37] op_sel_hi:[1,0]
	s_nop 0
	v_cvt_pk_bf16_f32 v4, v4, v5
	v_cvt_pk_bf16_f32 v5, v6, v7
	flat_store_dwordx2 v[34:35], v[4:5] offset:1024
	v_pk_mul_f32 v[2:3], v[2:3], v[54:55]
	v_pk_mul_f32 v[0:1], v[0:1], v[52:53]
	v_pk_mul_f32 v[2:3], v[2:3], v[36:37] op_sel_hi:[1,0]
	v_pk_mul_f32 v[0:1], v[0:1], v[36:37] op_sel_hi:[1,0]
	s_nop 0
	v_cvt_pk_bf16_f32 v0, v0, v1
	v_cvt_pk_bf16_f32 v1, v2, v3
	flat_store_dwordx2 v[34:35], v[0:1] offset:1536
	s_andn2_b64 exec, exec, s[8:9]
	s_cbranch_execz .LBB0_2527
; DI float bflo(unsigned u) { return __uint_as_float(u << 16); }
; DI float bfhi(unsigned u) { return __uint_as_float(u & 0xffff0000u); }
; DI void st16_wt(void* p, u32x4 v) { asm volatile("global_store_dwordx4 %0, %1, off sc0 sc1\n\ts_nop 1" :: "v"(p), "v"(v) : "memory"); }
; DI void row_phase(int wv, int mode, const float* X, const bf16_t* Y, const float* ga, float coef, const float* gb, float* Xout, bf16_t* A, int a_pad) {
;     ...
;         for (int j = 0; j < 4; ++j) v[j] = *(const f32x4*)(X + (size_t)r * DM + 4 * lane + 256 * j);
;         if (mode == 1) { f32x4 y[4]; float s = 0.f;
; #pragma unroll
;             for (int j = 0; j < 4; ++j) { const u32x2 yv = *(const u32x2*)(Y + (size_t)r * DM + 4 * lane + 256 * j); y[j] = (f32x4){bflo(yv.x), bfhi(yv.x), bflo(yv.y), bfhi(yv.y)}; s += y[j][0] * y[j][0] + y[j][1] * y[j][1] + y[j][2] * y[j][2] + y[j][3] * y[j][3]; }
;             const float rs = coef * rsqrtf(wave_sum(s) * (1.f / DM) + 1e-6f);
; #pragma unroll
;             for (int j = 0; j < 4; ++j) { const f32x4 gg = *(const f32x4*)(ga + 4 * lane + 256 * j); v[j] += y[j] * gg * rs; } }
;         if (Xout) {
; #pragma unroll
;             for (int j = 0; j < 4; ++j) st16_wt(Xout + (size_t)r * DM + 4 * lane + 256 * j, __builtin_bit_cast(u32x4, v[j])); }
;         if (gb) { float s = 0.f;
; #pragma unroll
;             for (int j = 0; j < 4; ++j) s += v[j][0] * v[j][0] + v[j][1] * v[j][1] + v[j][2] * v[j][2] + v[j][3] * v[j][3];
;             const float rs = rsqrtf(wave_sum(s) * (1.f / DM) + 1e-6f);
;             const size_t ar = a_pad ? (size_t)(r + (r >> 13) + 1) : (size_t)r;
; #pragma unroll
;             for (int j = 0; j < 4; ++j) { const f32x4 gg = *(const f32x4*)(gb + 4 * lane + 256 * j); const f32x4 o = v[j] * gg * rs;
.LBB0_2525:
	flat_load_dwordx2 v[46:47], v[24:25]
	flat_load_dwordx2 v[48:49], v[24:25] offset:512
	flat_load_dwordx2 v[50:51], v[24:25] offset:1024
	flat_load_dwordx2 v[52:53], v[24:25] offset:1536
	global_load_dwordx4 v[0:3], v[18:19], off
	global_load_dwordx4 v[4:7], v[18:19], off offset:1024
	global_load_dwordx4 v[8:11], v[18:19], off offset:2048
	global_load_dwordx4 v[12:15], v[18:19], off offset:3072
	global_load_dwordx4 v[30:33], v[26:27], off
	global_load_dwordx4 v[34:37], v[26:27], off offset:1024
	global_load_dwordx4 v[38:41], v[26:27], off offset:2048
	global_load_dwordx4 v[42:45], v[26:27], off offset:3072
	s_and_b64 vcc, exec, s[10:11]
	s_waitcnt vmcnt(0) lgkmcnt(0)
	v_and_b32_e32 v55, 0xffff0000, v46
	v_and_b32_e32 v57, 0xffff0000, v48
	v_lshlrev_b32_e32 v54, 16, v46
	v_lshlrev_b32_e32 v56, 16, v48
	v_and_b32_e32 v59, 0xffff0000, v50
	v_mul_f32_e32 v29, v55, v55
	v_mul_f32_e32 v64, v57, v57
	v_lshlrev_b32_e32 v46, 16, v47
	v_lshlrev_b32_e32 v48, 16, v49
	v_lshlrev_b32_e32 v58, 16, v50
	v_and_b32_e32 v61, 0xffff0000, v52
	v_mul_f32_e32 v65, v59, v59
	v_fmac_f32_e32 v29, v54, v54
	v_fmac_f32_e32 v64, v56, v56
	v_and_b32_e32 v47, 0xffff0000, v47
	v_and_b32_e32 v49, 0xffff0000, v49
	v_lshlrev_b32_e32 v50, 16, v51
	v_lshlrev_b32_e32 v60, 16, v52
	v_mul_f32_e32 v66, v61, v61
	v_fmac_f32_e32 v65, v58, v58
	v_fmac_f32_e32 v29, v46, v46
	v_fmac_f32_e32 v64, v48, v48
	v_and_b32_e32 v51, 0xffff0000, v51
	v_lshlrev_b32_e32 v52, 16, v53
	v_fmac_f32_e32 v66, v60, v60
	v_fmac_f32_e32 v65, v50, v50
	v_fmac_f32_e32 v29, v47, v47
	v_fmac_f32_e32 v64, v49, v49
	v_and_b32_e32 v53, 0xffff0000, v53
	v_pk_mul_f32 v[62:63], v[58:59], v[8:9]
	v_fmac_f32_e32 v66, v52, v52
	v_fmac_f32_e32 v65, v51, v51
	v_add_f32_e32 v8, v29, v64
	v_fmac_f32_e32 v66, v53, v53
	v_add_f32_e32 v8, v8, v65
	v_add_f32_e32 v8, v8, v66
	v_pk_mul_f32 v[0:1], v[54:55], v[0:1]
	v_pk_mul_f32 v[2:3], v[46:47], v[2:3]
	v_add_f32_dpp v8, v8, v8 quad_perm:[1,0,3,2] row_mask:0xf bank_mask:0xf bound_ctrl:1
	v_pk_mul_f32 v[4:5], v[56:57], v[4:5]
	v_pk_mul_f32 v[6:7], v[48:49], v[6:7]
	v_add_f32_dpp v8, v8, v8 quad_perm:[2,3,0,1] row_mask:0xf bank_mask:0xf bound_ctrl:1
	v_pk_mul_f32 v[46:47], v[50:51], v[10:11]
	v_pk_mul_f32 v[48:49], v[60:61], v[12:13]
	v_add_f32_dpp v8, v8, v8 row_half_mirror row_mask:0xf bank_mask:0xf bound_ctrl:1
	v_pk_mul_f32 v[50:51], v[52:53], v[14:15]
	s_nop 0
	v_add_f32_dpp v8, v8, v8 row_mirror row_mask:0xf bank_mask:0xf bound_ctrl:1
	v_mov_b32_e32 v9, v8
	s_nop 1
	v_permlane16_swap_b32_e32 v8, v9
	v_add_f32_e32 v8, v8, v9
	v_mov_b32_e32 v9, v8
	s_nop 1
	v_permlane32_swap_b32_e32 v8, v9
	v_add_f32_e32 v8, v8, v9
	v_fmamk_f32 v8, v8, 0x3a800000, v17
	v_mul_f32_e32 v9, 0x4b800000, v8
	v_cmp_gt_f32_e64 s[2:3], s22, v8
	s_nop 1
	v_cndmask_b32_e64 v8, v8, v9, s[2:3]
	v_rsq_f32_e32 v8, v8
	s_nop 0
	v_mul_f32_e32 v9, 0x45800000, v8
	v_cndmask_b32_e64 v8, v8, v9, s[2:3]
	v_mul_f32_e32 v52, 0.5, v8
	v_pk_fma_f32 v[14:15], v[2:3], v[52:53], v[32:33] op_sel_hi:[1,0,1]
	v_pk_fma_f32 v[12:13], v[0:1], v[52:53], v[30:31] op_sel_hi:[1,0,1]
	v_pk_fma_f32 v[10:11], v[6:7], v[52:53], v[36:37] op_sel_hi:[1,0,1]
	v_pk_fma_f32 v[8:9], v[4:5], v[52:53], v[34:35] op_sel_hi:[1,0,1]
	v_pk_fma_f32 v[6:7], v[46:47], v[52:53], v[40:41] op_sel_hi:[1,0,1]
	v_pk_fma_f32 v[4:5], v[62:63], v[52:53], v[38:39] op_sel_hi:[1,0,1]
	v_pk_fma_f32 v[2:3], v[50:51], v[52:53], v[44:45] op_sel_hi:[1,0,1]
	v_pk_fma_f32 v[0:1], v[48:49], v[52:53], v[42:43] op_sel_hi:[1,0,1]
	global_load_dwordx4 v[40:43], v[20:21], off
	global_load_dwordx4 v[44:47], v[20:21], off offset:1024
	global_load_dwordx4 v[48:51], v[20:21], off offset:2048
	global_load_dwordx4 v[52:55], v[20:21], off offset:3072
	s_cbranch_vccz .LBB0_2524
	global_store_dwordx4 v[26:27], v[12:15], off sc0 sc1
	s_nop 1
	v_lshl_add_u64 v[30:31], v[26:27], 0, s[16:17]
	global_store_dwordx4 v[30:31], v[8:11], off sc0 sc1
	s_nop 1
	v_lshl_add_u64 v[32:33], v[26:27], 0, s[18:19]
	global_store_dwordx4 v[32:33], v[4:7], off sc0 sc1
	s_nop 1
	v_lshl_add_u64 v[34:35], v[26:27], 0, s[20:21]
	global_store_dwordx4 v[34:35], v[0:3], off sc0 sc1
	s_nop 1
	s_branch .LBB0_2524

; DI unsigned pk2(float lo, float hi) { f32x2 v = {lo, hi}; bf16x2_t b = __builtin_convertvector(v, bf16x2_t); return __builtin_bit_cast(unsigned, b); }
; DI void row_phase(int wv, int mode, const float* X, const bf16_t* Y, const float* ga, float coef, const float* gb, float* Xout, bf16_t* A, int a_pad) {
;     ...
;         if (gb) { float s = 0.f;
; #pragma unroll
;             for (int j = 0; j < 4; ++j) s += v[j][0] * v[j][0] + v[j][1] * v[j][1] + v[j][2] * v[j][2] + v[j][3] * v[j][3];
;             const float rs = rsqrtf(wave_sum(s) * (1.f / DM) + 1e-6f);
;             const size_t ar = a_pad ? (size_t)(r + (r >> 13) + 1) : (size_t)r;
; #pragma unroll
;             for (int j = 0; j < 4; ++j) { const f32x4 gg = *(const f32x4*)(gb + 4 * lane + 256 * j); const f32x4 o = v[j] * gg * rs;
;                 u32x2 w; w.x = pk2(o[0], o[1]); w.y = pk2(o[2], o[3]); *(u32x2*)(A + ar * DM + 4 * lane + 256 * j) = w; } }
.LBB0_3475:
	v_mul_f32_e32 v36, v13, v13
	v_mul_f32_e32 v37, v9, v9
	v_mul_f32_e32 v38, v5, v5
	v_fmac_f32_e32 v36, v12, v12
	v_fmac_f32_e32 v37, v8, v8
	v_mul_f32_e32 v39, v1, v1
	v_fmac_f32_e32 v38, v4, v4
	v_fmac_f32_e32 v36, v14, v14
	v_fmac_f32_e32 v37, v10, v10
	v_fmac_f32_e32 v39, v0, v0
	v_fmac_f32_e32 v38, v6, v6
	v_fmac_f32_e32 v36, v15, v15
	v_fmac_f32_e32 v37, v11, v11
	v_fmac_f32_e32 v39, v2, v2
	v_fmac_f32_e32 v38, v7, v7
	v_add_f32_e32 v36, v36, v37
	v_fmac_f32_e32 v39, v3, v3
	v_add_f32_e32 v36, v38, v36
	v_add_f32_e32 v36, v39, v36
	v_lshl_add_u64 v[34:35], v[24:25], 0, v[18:19]
	v_add_co_u32_e64 v34, s[2:3], s19, v34
	v_add_f32_dpp v36, v36, v36 quad_perm:[1,0,3,2] row_mask:0xf bank_mask:0xf bound_ctrl:1
	s_nop 0
	v_addc_co_u32_e64 v35, s[2:3], 0, v35, s[2:3]
	v_add_f32_dpp v36, v36, v36 quad_perm:[2,3,0,1] row_mask:0xf bank_mask:0xf bound_ctrl:1
	v_add_u32_e32 v16, s56, v16
	v_lshl_add_u64 v[24:25], v[24:25], 0, s[8:9]
	v_add_f32_dpp v36, v36, v36 row_half_mirror row_mask:0xf bank_mask:0xf bound_ctrl:1
	v_lshl_add_u64 v[26:27], v[26:27], 0, s[8:9]
	v_lshl_add_u64 v[28:29], v[28:29], 0, s[10:11]
	v_add_f32_dpp v36, v36, v36 row_mirror row_mask:0xf bank_mask:0xf bound_ctrl:1
	v_mov_b32_e32 v37, v36
	s_nop 1
	v_permlane16_swap_b32_e32 v36, v37
	v_add_f32_e32 v36, v36, v37
	v_mov_b32_e32 v37, v36
	s_nop 1
	v_permlane32_swap_b32_e32 v36, v37
	v_add_f32_e32 v36, v36, v37
	v_fmamk_f32 v36, v36, 0x3a800000, v17
	v_mul_f32_e32 v37, 0x4b800000, v36
	v_cmp_gt_f32_e32 vcc, s18, v36
	s_waitcnt vmcnt(0)
	v_pk_mul_f32 v[14:15], v[14:15], v[42:43]
	v_cndmask_b32_e32 v36, v36, v37, vcc
	v_rsq_f32_e32 v36, v36
	v_pk_mul_f32 v[12:13], v[12:13], v[40:41]
	v_mul_f32_e32 v37, 0x45800000, v36
	v_cndmask_b32_e32 v36, v36, v37, vcc
	v_pk_mul_f32 v[14:15], v[14:15], v[36:37] op_sel_hi:[1,0]
	v_pk_mul_f32 v[12:13], v[12:13], v[36:37] op_sel_hi:[1,0]
	v_cmp_lt_i32_e32 vcc, s20, v16
	v_cvt_pk_bf16_f32 v12, v12, v13
	v_cvt_pk_bf16_f32 v13, v14, v15
	flat_store_dwordx2 v[34:35], v[12:13]
	s_or_b64 s[6:7], vcc, s[6:7]
	v_pk_mul_f32 v[10:11], v[10:11], v[46:47]
	v_pk_mul_f32 v[8:9], v[8:9], v[44:45]
	v_pk_mul_f32 v[10:11], v[10:11], v[36:37] op_sel_hi:[1,0]
	v_pk_mul_f32 v[8:9], v[8:9], v[36:37] op_sel_hi:[1,0]
	s_nop 0
	v_cvt_pk_bf16_f32 v8, v8, v9
	v_cvt_pk_bf16_f32 v9, v10, v11
	flat_store_dwordx2 v[34:35], v[8:9] offset:512
	v_pk_mul_f32 v[6:7], v[6:7], v[50:51]
	v_pk_mul_f32 v[4:5], v[4:5], v[48:49]
	v_pk_mul_f32 v[6:7], v[6:7], v[36:37] op_sel_hi:[1,0]
	v_pk_mul_f32 v[4:5], v[4:5], v[36:37] op_sel_hi:[1,0]
	s_nop 0
	v_cvt_pk_bf16_f32 v4, v4, v5
	v_cvt_pk_bf16_f32 v5, v6, v7
	flat_store_dwordx2 v[34:35], v[4:5] offset:1024
	v_pk_mul_f32 v[2:3], v[2:3], v[54:55]
	v_pk_mul_f32 v[0:1], v[0:1], v[52:53]
	v_pk_mul_f32 v[2:3], v[2:3], v[36:37] op_sel_hi:[1,0]
	v_pk_mul_f32 v[0:1], v[0:1], v[36:37] op_sel_hi:[1,0]
	s_nop 0
	v_cvt_pk_bf16_f32 v0, v0, v1
	v_cvt_pk_bf16_f32 v1, v2, v3
	flat_store_dwordx2 v[34:35], v[0:1] offset:1536
	s_andn2_b64 exec, exec, s[6:7]
	s_cbranch_execz .LBB0_3478
; DI float bflo(unsigned u) { return __uint_as_float(u << 16); }
; DI float bfhi(unsigned u) { return __uint_as_float(u & 0xffff0000u); }
; DI void st16_wt(void* p, u32x4 v) { asm volatile("global_store_dwordx4 %0, %1, off sc0 sc1\n\ts_nop 1" :: "v"(p), "v"(v) : "memory"); }
; DI void row_phase(int wv, int mode, const float* X, const bf16_t* Y, const float* ga, float coef, const float* gb, float* Xout, bf16_t* A, int a_pad) {
;     ...
;         for (int j = 0; j < 4; ++j) v[j] = *(const f32x4*)(X + (size_t)r * DM + 4 * lane + 256 * j);
;         if (mode == 1) { f32x4 y[4]; float s = 0.f;
; #pragma unroll
;             for (int j = 0; j < 4; ++j) { const u32x2 yv = *(const u32x2*)(Y + (size_t)r * DM + 4 * lane + 256 * j); y[j] = (f32x4){bflo(yv.x), bfhi(yv.x), bflo(yv.y), bfhi(yv.y)}; s += y[j][0] * y[j][0] + y[j][1] * y[j][1] + y[j][2] * y[j][2] + y[j][3] * y[j][3]; }
;             const float rs = coef * rsqrtf(wave_sum(s) * (1.f / DM) + 1e-6f);
; #pragma unroll
;             for (int j = 0; j < 4; ++j) { const f32x4 gg = *(const f32x4*)(ga + 4 * lane + 256 * j); v[j] += y[j] * gg * rs; } }
;         if (Xout) {
; #pragma unroll
;             for (int j = 0; j < 4; ++j) st16_wt(Xout + (size_t)r * DM + 4 * lane + 256 * j, __builtin_bit_cast(u32x4, v[j])); }
;         if (gb) { float s = 0.f;
; #pragma unroll
;             for (int j = 0; j < 4; ++j) s += v[j][0] * v[j][0] + v[j][1] * v[j][1] + v[j][2] * v[j][2] + v[j][3] * v[j][3];
;             const float rs = rsqrtf(wave_sum(s) * (1.f / DM) + 1e-6f);
;             const size_t ar = a_pad ? (size_t)(r + (r >> 13) + 1) : (size_t)r;
; #pragma unroll
;             for (int j = 0; j < 4; ++j) { const f32x4 gg = *(const f32x4*)(gb + 4 * lane + 256 * j); const f32x4 o = v[j] * gg * rs;
.LBB0_3476:
	v_lshl_add_u64 v[0:1], v[26:27], 0, v[18:19]
	v_add_co_u32_e32 v46, vcc, 0x7000000, v0
	s_nop 1
	v_addc_co_u32_e32 v47, vcc, 0, v1, vcc
	flat_load_dwordx2 v[48:49], v[46:47]
	flat_load_dwordx2 v[50:51], v[46:47] offset:512
	flat_load_dwordx2 v[52:53], v[46:47] offset:1024
	flat_load_dwordx2 v[54:55], v[46:47] offset:1536
	global_load_dwordx4 v[0:3], v[20:21], off
	global_load_dwordx4 v[4:7], v[20:21], off offset:1024
	global_load_dwordx4 v[8:11], v[20:21], off offset:2048
	global_load_dwordx4 v[12:15], v[20:21], off offset:3072
	global_load_dwordx4 v[30:33], v[28:29], off
	global_load_dwordx4 v[34:37], v[28:29], off offset:1024
	global_load_dwordx4 v[38:41], v[28:29], off offset:2048
	global_load_dwordx4 v[42:45], v[28:29], off offset:3072
	s_and_b64 vcc, exec, s[0:1]
	s_waitcnt vmcnt(0) lgkmcnt(0)
	v_and_b32_e32 v47, 0xffff0000, v48
	v_and_b32_e32 v57, 0xffff0000, v50
	v_lshlrev_b32_e32 v46, 16, v48
	v_lshlrev_b32_e32 v56, 16, v50
	v_and_b32_e32 v59, 0xffff0000, v52
	v_mul_f32_e32 v64, v47, v47
	v_mul_f32_e32 v65, v57, v57
	v_lshlrev_b32_e32 v48, 16, v49
	v_lshlrev_b32_e32 v50, 16, v51
	v_lshlrev_b32_e32 v58, 16, v52
	v_and_b32_e32 v61, 0xffff0000, v54
	v_mul_f32_e32 v66, v59, v59
	v_fmac_f32_e32 v64, v46, v46
	v_fmac_f32_e32 v65, v56, v56
	v_and_b32_e32 v49, 0xffff0000, v49
	v_and_b32_e32 v51, 0xffff0000, v51
	v_lshlrev_b32_e32 v52, 16, v53
	v_lshlrev_b32_e32 v60, 16, v54
	v_mul_f32_e32 v67, v61, v61
	v_fmac_f32_e32 v66, v58, v58
	v_fmac_f32_e32 v64, v48, v48
	v_fmac_f32_e32 v65, v50, v50
	v_and_b32_e32 v53, 0xffff0000, v53
	v_lshlrev_b32_e32 v54, 16, v55
	v_fmac_f32_e32 v67, v60, v60
	v_fmac_f32_e32 v66, v52, v52
	v_fmac_f32_e32 v64, v49, v49
	v_fmac_f32_e32 v65, v51, v51
	v_and_b32_e32 v55, 0xffff0000, v55
	v_pk_mul_f32 v[62:63], v[58:59], v[8:9]
	v_fmac_f32_e32 v67, v54, v54
	v_fmac_f32_e32 v66, v53, v53
	v_add_f32_e32 v8, v64, v65
	v_fmac_f32_e32 v67, v55, v55
	v_add_f32_e32 v8, v8, v66
	v_add_f32_e32 v8, v8, v67
	v_pk_mul_f32 v[0:1], v[46:47], v[0:1]
	v_pk_mul_f32 v[2:3], v[48:49], v[2:3]
	v_add_f32_dpp v8, v8, v8 quad_perm:[1,0,3,2] row_mask:0xf bank_mask:0xf bound_ctrl:1
	v_pk_mul_f32 v[4:5], v[56:57], v[4:5]
	v_pk_mul_f32 v[6:7], v[50:51], v[6:7]
	v_add_f32_dpp v8, v8, v8 quad_perm:[2,3,0,1] row_mask:0xf bank_mask:0xf bound_ctrl:1
	v_pk_mul_f32 v[46:47], v[52:53], v[10:11]
	v_pk_mul_f32 v[48:49], v[60:61], v[12:13]
	v_add_f32_dpp v8, v8, v8 row_half_mirror row_mask:0xf bank_mask:0xf bound_ctrl:1
	v_pk_mul_f32 v[50:51], v[54:55], v[14:15]
	s_nop 0
	v_add_f32_dpp v8, v8, v8 row_mirror row_mask:0xf bank_mask:0xf bound_ctrl:1
	v_mov_b32_e32 v9, v8
	s_nop 1
	v_permlane16_swap_b32_e32 v8, v9
	v_add_f32_e32 v8, v8, v9
	v_mov_b32_e32 v9, v8
	s_nop 1
	v_permlane32_swap_b32_e32 v8, v9
	v_add_f32_e32 v8, v8, v9
	v_fmamk_f32 v8, v8, 0x3a800000, v17
	v_mul_f32_e32 v9, 0x4b800000, v8
	v_cmp_gt_f32_e64 s[2:3], s18, v8
	s_nop 1
	v_cndmask_b32_e64 v8, v8, v9, s[2:3]
	v_rsq_f32_e32 v8, v8
	s_nop 0
	v_mul_f32_e32 v9, 0x45800000, v8
	v_cndmask_b32_e64 v52, v8, v9, s[2:3]
	v_pk_fma_f32 v[14:15], v[2:3], v[52:53], v[32:33] op_sel_hi:[1,0,1]
	v_pk_fma_f32 v[12:13], v[0:1], v[52:53], v[30:31] op_sel_hi:[1,0,1]
	v_pk_fma_f32 v[10:11], v[6:7], v[52:53], v[36:37] op_sel_hi:[1,0,1]
	v_pk_fma_f32 v[8:9], v[4:5], v[52:53], v[34:35] op_sel_hi:[1,0,1]
	v_pk_fma_f32 v[6:7], v[46:47], v[52:53], v[40:41] op_sel_hi:[1,0,1]
	v_pk_fma_f32 v[4:5], v[62:63], v[52:53], v[38:39] op_sel_hi:[1,0,1]
	v_pk_fma_f32 v[2:3], v[50:51], v[52:53], v[44:45] op_sel_hi:[1,0,1]
	v_pk_fma_f32 v[0:1], v[48:49], v[52:53], v[42:43] op_sel_hi:[1,0,1]
	global_load_dwordx4 v[40:43], v[22:23], off
	global_load_dwordx4 v[44:47], v[22:23], off offset:1024
	global_load_dwordx4 v[48:51], v[22:23], off offset:2048
	global_load_dwordx4 v[52:55], v[22:23], off offset:3072
	s_cbranch_vccnz .LBB0_3475
	global_store_dwordx4 v[28:29], v[12:15], off sc0 sc1
	s_nop 1
	v_lshl_add_u64 v[30:31], v[28:29], 0, s[12:13]
	global_store_dwordx4 v[30:31], v[8:11], off sc0 sc1
	s_nop 1
	v_lshl_add_u64 v[32:33], v[28:29], 0, s[14:15]
	global_store_dwordx4 v[32:33], v[4:7], off sc0 sc1
	s_nop 1
	v_lshl_add_u64 v[34:35], v[28:29], 0, s[16:17]
	global_store_dwordx4 v[34:35], v[0:3], off sc0 sc1
	s_nop 1
	s_branch .LBB0_3475
